# static s_setprio 1 for waves 4-7 during MLA prompt items (reset to 0 at item end)
# speedup vs baseline: 1.0015x; 1.0015x over previous
; DI void mla_item(const P& p, char* smem, int b, int hd, int q0, bool samp) {
;   int tid = threadIdx.x; asm volatile("" : "+v"(tid));
;   const int w = __builtin_amdgcn_readfirstlane(tid >> 6), lane = tid & 63, l32 = lane & 31, lh = lane >> 5;
;   const bool active = samp ? (w < 4) : true;
;   const int hw = samp ? hd + (w >> 1) : hd;
;   const int qw0 = samp ? (w & 1) * 32 : q0 + w * 32;
;   constexpr int STG = 2 * MLA_STAGE;
;   const int hoff = samp ? (w >> 1) * MLA_STAGE : 0;
;   const size_t tokrow0 = samp ? (size_t)(NTOK_P + b * 64) : (size_t)b * 2048;
;   const int nkb_blk = samp ? 65 : (q0 / 64 + 4);
;   const int nkb_w = samp ? 65 : (qw0 / 64 + 1);
;   const u16* kv = (const u16*)(p.ws + OFF_KV);
;   const u16* krope = (const u16*)(p.ws + OFF_KROPE);
;   bf16x8 qf[6];
;   if (active) {
;     const u16* qp = (const u16*)(p.ws + OFF_QMLA) + (tokrow0 + qw0 + l32) * 768 + hw * 96 + lh * 8;
; #pragma unroll
;     for (int ks = 0; ks < 6; ++ks) qf[ks] = *(const bf16x8*)(qp + ks * 16);
.LBB0_393:
	s_and_b64 vcc, exec, s[4:5]
	s_cbranch_vccz .LBB0_426
	s_add_i32 s4, s85, 0xffffff40
	s_and_b32 s5, s4, 0xffffff00
	v_mov_b32_e32 v1, v152
	s_sub_i32 s60, 0x700, s5
	s_lshl_b32 s62, s4, 8
	v_readfirstlane_b32 s5, v1
	s_cmp_lt_u32 s5, 0x100
	s_cbranch_scc1 .Lmla_prio_skip
	s_setprio 1
.Lmla_prio_skip:
	s_ashr_i32 s5, s5, 1
	s_and_b32 s61, s5, 0xffffffe0
	s_add_i32 s61, s61, s60
	v_and_b32_e32 v14, 31, v1
	s_ashr_i32 s63, s61, 31
	s_and_b32 s46, s62, 0xf800
	v_or_b32_e32 v4, s61, v14
	v_mov_b32_e32 v5, s63
	v_lshl_add_u64 v[104:105], v[4:5], 0, s[46:47]
	v_mov_b64_e32 v[4:5], s[36:37]
	v_mad_u64_u32 v[4:5], s[4:5], v104, s76, v[4:5]
	v_bfe_u32 v146, v1, 5, 1
	v_mad_i32_i24 v5, v105, s76, v5
	s_mul_i32 s4, s86, 0xc0
	s_mov_b32 s5, s47
	v_lshl_add_u64 v[4:5], v[4:5], 0, s[4:5]
	v_lshlrev_b32_e32 v106, 4, v146
	v_mov_b32_e32 v107, v3
	v_ashrrev_i32_e32 v44, 3, v1
	v_lshl_add_u64 v[4:5], v[4:5], 0, v[106:107]
	v_ashrrev_i32_e32 v45, 31, v44
	global_load_dwordx4 v[88:91], v[4:5], off
	global_load_dwordx4 v[84:87], v[4:5], off offset:32
	global_load_dwordx4 v[80:83], v[4:5], off offset:64
	global_load_dwordx4 v[76:79], v[4:5], off offset:96
	global_load_dwordx4 v[72:75], v[4:5], off offset:128
	global_load_dwordx4 v[68:71], v[4:5], off offset:160
	v_lshl_add_u64 v[4:5], v[44:45], 0, s[46:47]
	v_lshlrev_b64 v[4:5], 11, v[4:5]
	v_lshlrev_b32_e32 v12, 3, v1
	v_lshl_add_u64 v[4:5], s[26:27], 0, v[4:5]
	s_lshl_b32 s52, s86, 8
	s_mov_b32 s53, s47
	v_and_b32_e32 v2, 56, v12
	v_lshl_add_u64 v[4:5], v[4:5], 0, s[52:53]
	v_lshlrev_b32_e32 v2, 1, v2
	v_lshl_add_u64 v[4:5], v[4:5], 0, v[2:3]
	global_load_dwordx4 v[8:11], v[4:5], off
	s_nop 0
	global_load_dwordx4 v[4:7], v[4:5], off offset:128
	v_and_b32_e32 v12, 24, v12
	v_cmp_lt_i32_e32 vcc, s73, v1
	v_cmp_gt_i32_e64 s[4:5], s77, v1
	s_waitcnt vmcnt(10)
	v_mov_b32_e32 v92, v3
	v_mov_b32_e32 v93, v3
	v_mov_b32_e32 v94, v3
	v_mov_b32_e32 v95, v3
	v_ashrrev_i32_e32 v15, 2, v1
	v_lshlrev_b32_e32 v12, 1, v12
	s_and_saveexec_b64 s[6:7], s[4:5]
	s_cbranch_execz .LBB0_396
	v_ashrrev_i32_e32 v16, 2, v1
	v_ashrrev_i32_e32 v17, 31, v16
	v_lshl_add_u64 v[16:17], v[16:17], 0, s[46:47]
	v_lshlrev_b64 v[16:17], 6, v[16:17]
	v_lshl_add_u64 v[16:17], s[34:35], 0, v[16:17]
	v_mov_b32_e32 v13, v3
	v_lshl_add_u64 v[16:17], v[16:17], 0, v[12:13]
	global_load_dwordx4 v[92:95], v[16:17], off

; DI float bflo(unsigned v) { return __uint_as_float(v << 16); }
; DI float bfhi(unsigned v) { return __uint_as_float(v & 0xffff0000u); }
; DI void store_o(const P& p, const f32x16 (&o)[2], float inv, size_t tok, int colbase, int lh) {
;   const u16* gates = (const u16*)(p.ws + OFF_GATES);
;   u16* mixed = (u16*)(p.ws + OFF_H);
; #pragma unroll
;   for (int dvt = 0; dvt < 2; ++dvt)
; #pragma unroll
;     for (int g = 0; g < 4; ++g) {
;       const size_t off = tok * 1024 + colbase + dvt * 32 + g * 8 + lh * 4;
;       const u32x2 gt = *(const u32x2*)(gates + off);
;       u32x2 ov = {pk2(o[dvt][4 * g + 0] * inv * bflo(gt.x), o[dvt][4 * g + 1] * inv * bfhi(gt.x)),
;                   pk2(o[dvt][4 * g + 2] * inv * bflo(gt.y), o[dvt][4 * g + 3] * inv * bfhi(gt.y))};
;       *(u32x2*)(mixed + off) = ov;
;     }
; }
; DI void mla_item(const P& p, char* smem, int b, int hd, int q0, bool samp) {
;     ...
;   if (active) {
;     const float lt = lsum + __shfl_xor(lsum, 32);
;     store_o(p, o, 1.f / lt, tokrow0 + qw0 + l32, 512 + hw * 64, lh);
;   }
.LBB0_425:
	s_lshl_b32 s4, s86, 6
	v_lshlrev_b64 v[52:53], 10, v[104:105]
	v_lshlrev_b32_e32 v1, 2, v146
	v_or3_b32 v1, v52, s4, v1
	v_or_b32_e32 v52, 0x200, v1
	v_lshlrev_b64 v[36:37], 1, v[52:53]
	v_lshl_add_u64 v[38:39], s[22:23], 0, v[36:37]
	v_or_b32_e32 v40, 16, v36
	v_mov_b32_e32 v41, v37
	s_barrier
	s_setprio 0
	global_load_dwordx2 v[38:39], v[38:39], off
	v_lshl_add_u64 v[42:43], s[22:23], 0, v[40:41]
	global_load_dwordx2 v[42:43], v[42:43], off
	v_or_b32_e32 v44, 32, v36
	v_mov_b32_e32 v45, v37
	v_lshl_add_u64 v[46:47], s[22:23], 0, v[44:45]
	global_load_dwordx2 v[46:47], v[46:47], off
	v_or_b32_e32 v48, 48, v36
	v_mov_b32_e32 v49, v37
	v_lshl_add_u64 v[50:51], s[22:23], 0, v[48:49]
	global_load_dwordx2 v[50:51], v[50:51], off
	v_or_b32_e32 v56, 64, v36
	v_mov_b32_e32 v57, v37
	v_lshl_add_u64 v[54:55], s[22:23], 0, v[56:57]
	global_load_dwordx2 v[58:59], v[54:55], off
	v_or_b32_e32 v62, 0x50, v36
	v_mov_b32_e32 v63, v37
	v_lshl_add_u64 v[54:55], s[22:23], 0, v[62:63]
	global_load_dwordx2 v[64:65], v[54:55], off
	v_and_b32_e32 v52, 64, v154
	v_xor_b32_e32 v2, 32, v154
	v_add_u32_e32 v52, 64, v52
	v_cmp_lt_i32_e32 vcc, v2, v52
	v_or_b32_e32 v52, 0x238, v1
	v_lshl_add_u64 v[60:61], s[24:25], 0, v[36:37]
	v_or_b32_e32 v36, 0x60, v36
	v_lshl_add_u64 v[54:55], v[52:53], 1, s[22:23]
	v_lshl_add_u64 v[66:67], s[22:23], 0, v[36:37]
	global_load_dwordx2 v[66:67], v[66:67], off
	s_nop 0
	global_load_dwordx2 v[54:55], v[54:55], off
	v_cndmask_b32_e32 v2, v154, v2, vcc
	v_lshlrev_b32_e32 v2, 2, v2
	ds_bpermute_b32 v1, v2, v149
	v_lshl_add_u64 v[40:41], s[24:25], 0, v[40:41]
	s_mov_b64 s[52:53], -1
	s_waitcnt lgkmcnt(0)
	v_add_f32_e32 v1, v149, v1
	v_div_scale_f32 v2, s[4:5], v1, v1, 1.0
	v_rcp_f32_e32 v68, v2
	v_div_scale_f32 v69, vcc, 1.0, v1, 1.0
	v_fma_f32 v70, -v2, v68, 1.0
	v_fmac_f32_e32 v68, v70, v68
	v_mul_f32_e32 v70, v69, v68
	v_fma_f32 v71, -v2, v70, v69
	v_fmac_f32_e32 v70, v71, v68
	v_fma_f32 v2, -v2, v70, v69
	v_div_fmas_f32 v2, v2, v68, v70
	v_div_fixup_f32 v2, v2, v1, 1.0
	v_pk_mul_f32 v[20:21], v[20:21], v[2:3] op_sel_hi:[1,0]
	v_pk_mul_f32 v[22:23], v[22:23], v[2:3] op_sel_hi:[1,0]
	v_pk_mul_f32 v[24:25], v[24:25], v[2:3] op_sel_hi:[1,0]
	v_pk_mul_f32 v[26:27], v[26:27], v[2:3] op_sel_hi:[1,0]
	v_pk_mul_f32 v[28:29], v[28:29], v[2:3] op_sel_hi:[1,0]
	v_pk_mul_f32 v[30:31], v[30:31], v[2:3] op_sel_hi:[1,0]
	v_pk_mul_f32 v[4:5], v[4:5], v[2:3] op_sel_hi:[1,0]
	v_pk_mul_f32 v[6:7], v[6:7], v[2:3] op_sel_hi:[1,0]
	s_waitcnt vmcnt(7)
	v_lshlrev_b32_e32 v68, 16, v38
	v_and_b32_e32 v69, 0xffff0000, v38
	v_lshlrev_b32_e32 v38, 16, v39
	v_and_b32_e32 v39, 0xffff0000, v39
	v_pk_mul_f32 v[20:21], v[20:21], v[68:69]
	v_pk_mul_f32 v[22:23], v[22:23], v[38:39]
	s_waitcnt vmcnt(6)
	v_lshlrev_b32_e32 v38, 16, v42
	v_and_b32_e32 v39, 0xffff0000, v42
	v_lshlrev_b32_e32 v42, 16, v43
	v_and_b32_e32 v43, 0xffff0000, v43
	v_cvt_pk_bf16_f32 v20, v20, v21
	v_cvt_pk_bf16_f32 v21, v22, v23
	v_pk_mul_f32 v[22:23], v[24:25], v[38:39]
	v_pk_mul_f32 v[24:25], v[26:27], v[42:43]
	s_waitcnt vmcnt(5)
	v_lshlrev_b32_e32 v68, 16, v46
	v_and_b32_e32 v69, 0xffff0000, v46
	v_lshlrev_b32_e32 v46, 16, v47
	global_store_dwordx2 v[60:61], v[20:21], off
	v_cvt_pk_bf16_f32 v20, v22, v23
	v_cvt_pk_bf16_f32 v21, v24, v25
	v_and_b32_e32 v47, 0xffff0000, v47
	v_pk_mul_f32 v[26:27], v[28:29], v[68:69]
	global_store_dwordx2 v[40:41], v[20:21], off
	v_pk_mul_f32 v[20:21], v[30:31], v[46:47]
	v_cvt_pk_bf16_f32 v22, v26, v27
	v_cvt_pk_bf16_f32 v23, v20, v21
	v_lshl_add_u64 v[20:21], s[24:25], 0, v[44:45]
	global_store_dwordx2 v[20:21], v[22:23], off
	v_pk_mul_f32 v[20:21], v[32:33], v[2:3] op_sel_hi:[1,0]
	s_waitcnt vmcnt(7)
	v_lshlrev_b32_e32 v22, 16, v50
	v_and_b32_e32 v23, 0xffff0000, v50
	v_pk_mul_f32 v[20:21], v[20:21], v[22:23]
	v_pk_mul_f32 v[22:23], v[34:35], v[2:3] op_sel_hi:[1,0]
	v_lshlrev_b32_e32 v24, 16, v51
	v_and_b32_e32 v25, 0xffff0000, v51
	v_pk_mul_f32 v[22:23], v[22:23], v[24:25]
	v_cvt_pk_bf16_f32 v20, v20, v21
	v_cvt_pk_bf16_f32 v21, v22, v23
	v_lshl_add_u64 v[22:23], s[24:25], 0, v[48:49]
	global_store_dwordx2 v[22:23], v[20:21], off
	s_waitcnt vmcnt(7)
	v_lshlrev_b32_e32 v20, 16, v58
	v_and_b32_e32 v21, 0xffff0000, v58
	v_pk_mul_f32 v[4:5], v[4:5], v[20:21]
	v_lshlrev_b32_e32 v20, 16, v59
	v_and_b32_e32 v21, 0xffff0000, v59
	v_pk_mul_f32 v[6:7], v[6:7], v[20:21]
	v_cvt_pk_bf16_f32 v4, v4, v5
	v_cvt_pk_bf16_f32 v5, v6, v7
	v_lshl_add_u64 v[6:7], s[24:25], 0, v[56:57]
	global_store_dwordx2 v[6:7], v[4:5], off
	v_pk_mul_f32 v[4:5], v[8:9], v[2:3] op_sel_hi:[1,0]
	s_waitcnt vmcnt(7)
	v_lshlrev_b32_e32 v6, 16, v64
	v_and_b32_e32 v7, 0xffff0000, v64
	v_pk_mul_f32 v[4:5], v[4:5], v[6:7]
	v_pk_mul_f32 v[6:7], v[10:11], v[2:3] op_sel_hi:[1,0]
	v_lshlrev_b32_e32 v8, 16, v65
	v_and_b32_e32 v9, 0xffff0000, v65
	v_pk_mul_f32 v[6:7], v[6:7], v[8:9]
	v_cvt_pk_bf16_f32 v4, v4, v5
	v_cvt_pk_bf16_f32 v5, v6, v7
	v_lshl_add_u64 v[6:7], s[24:25], 0, v[62:63]
	global_store_dwordx2 v[6:7], v[4:5], off
	v_pk_mul_f32 v[4:5], v[12:13], v[2:3] op_sel_hi:[1,0]
	s_waitcnt vmcnt(7)
	v_lshlrev_b32_e32 v6, 16, v66
	v_and_b32_e32 v7, 0xffff0000, v66
	v_pk_mul_f32 v[4:5], v[4:5], v[6:7]
	v_pk_mul_f32 v[6:7], v[14:15], v[2:3] op_sel_hi:[1,0]
	v_lshlrev_b32_e32 v8, 16, v67
	v_and_b32_e32 v9, 0xffff0000, v67
	v_pk_mul_f32 v[6:7], v[6:7], v[8:9]
	v_cvt_pk_bf16_f32 v4, v4, v5
	v_cvt_pk_bf16_f32 v5, v6, v7
	v_lshl_add_u64 v[6:7], s[24:25], 0, v[36:37]
	global_store_dwordx2 v[6:7], v[4:5], off
	v_pk_mul_f32 v[4:5], v[16:17], v[2:3] op_sel_hi:[1,0]
	s_waitcnt vmcnt(7)
	v_lshlrev_b32_e32 v6, 16, v54
	v_and_b32_e32 v7, 0xffff0000, v54
	v_pk_mul_f32 v[4:5], v[4:5], v[6:7]
	s_nop 0
	v_cvt_pk_bf16_f32 v56, v4, v5
	v_mul_f32_e32 v4, v18, v2
	v_lshlrev_b32_e32 v18, 16, v55
	v_mov_b32_e32 v5, v2
	v_pk_mul_f32 v[18:19], v[4:5], v[18:19]
